# a14 + P12 epilogue: SSQP row loads of 4 row groups issued together, 2nd batch behind the math; ret_out: gate loads issued at item start, no store-drain ladder
# baseline (speedup 1.0000x reference)
.LBB0_862:
	s_or_b64 exec, exec, s[0:1]
	s_add_u32 s16, s26, 0xde00000
	s_addc_u32 s17, s27, 0
	s_add_u32 s20, s26, 0x8900000
	s_addc_u32 s21, s27, 0
	s_andn2_b64 vcc, exec, s[6:7]
	s_waitcnt lgkmcnt(0)
	s_barrier
	v_mbcnt_lo_u32_b32 v0, -1, 0
	v_mbcnt_hi_u32_b32 v0, -1, v0
	s_cbranch_vccnz .LBB0_871
	s_and_b32 s64, s2, 7
	s_lshl_b32 s64, s64, 7
	s_lshr_b32 s67, s2, 3
	s_or_b32 s64, s64, s67
	s_mov_b32 s66, 32
	s_cmp_eq_u32 s28, 0x100
	s_cselect_b32 s64, s64, s2
	s_cselect_b32 s66, s66, s28
	s_ashr_i32 s65, s64, 31
	s_add_u32 s6, s26, 0x5900000
	s_addc_u32 s7, s27, 0
	s_ashr_i32 s0, s64, 9
	s_and_b32 s3, s64, 63
	s_ashr_i32 s1, s0, 31
	v_add_u32_e32 v1, s33, v0
	s_bfe_u32 s34, s64, 0x30006
	s_lshl_b64 s[8:9], s[0:1], 13
	s_lshl_b32 s0, s3, 7
	v_ashrrev_i32_e32 v106, 3, v1
	s_or_b32 s8, s8, s0
	s_lshl_b32 s0, s34, 7
	v_ashrrev_i32_e32 v107, 31, v106
	s_add_u32 s22, s6, s0
	v_lshlrev_b32_e32 v4, 4, v0
	v_lshl_add_u64 v[2:3], s[8:9], 0, v[106:107]
	s_addc_u32 s23, s7, 0
	v_and_b32_e32 v108, 0x70, v4
	v_mov_b32_e32 v109, 0
	v_lshl_add_u64 v[4:5], s[22:23], 0, v[108:109]
	v_lshlrev_b64 v[2:3], 10, v[2:3]
	v_lshl_add_u64 v[2:3], v[4:5], 0, v[2:3]
	s_mov_b32 s23, 0x10000
	v_and_b32_e32 v104, 0x7f, v1
	v_add_co_u32_e32 v4, vcc, s23, v2
	v_ashrrev_i32_e32 v12, 7, v1
	s_nop 0
	v_addc_co_u32_e32 v5, vcc, 0, v3, vcc
	global_load_dwordx4 v[48:51], v[2:3], off
	global_load_dwordx4 v[52:55], v[4:5], off
	v_or_b32_e32 v2, s8, v104
	v_mov_b32_e32 v3, s9
	v_lshlrev_b64 v[2:3], 11, v[2:3]
	s_mov_b32 s1, 0
	v_lshl_add_u64 v[2:3], s[12:13], 0, v[2:3]
	s_lshl_b32 s0, s34, 8
	v_lshlrev_b32_e32 v110, 3, v12
	s_ashr_i32 s3, s2, 31
	v_lshl_add_u64 v[2:3], v[2:3], 0, s[0:1]
	v_ashrrev_i32_e32 v111, 31, v110
	s_lshl_b64 s[8:9], s[64:65], 14
	v_lshl_add_u64 v[2:3], v[110:111], 1, v[2:3]
	s_add_u32 s8, s18, s8
	global_load_dwordx4 v[56:59], v[2:3], off
	global_load_dwordx4 v[60:63], v[2:3], off offset:64
	global_load_dwordx4 v[64:67], v[2:3], off offset:128
	global_load_dwordx4 v[68:71], v[2:3], off offset:192
	s_addc_u32 s9, s19, s9
	s_add_i32 s34, s64, 0x400
	v_lshlrev_b32_e32 v2, 6, v106
	s_ashr_i32 s35, s34, 31
	v_ashrrev_i32_e32 v3, 31, v2
	s_lshl_b64 s[34:35], s[34:35], 14
	v_lshlrev_b64 v[112:113], 1, v[2:3]
	v_add_u32_e32 v2, 0x1000, v2
	s_add_u32 s34, s18, s34
	v_ashrrev_i32_e32 v3, 31, v2
	s_addc_u32 s35, s19, s35
	v_lshl_add_u64 v[4:5], s[8:9], 0, v[108:109]
	v_lshlrev_b64 v[114:115], 1, v[2:3]
	v_lshl_add_u64 v[6:7], s[34:35], 0, v[108:109]
	v_lshl_add_u64 v[8:9], v[4:5], 0, v[112:113]
	v_lshl_add_u64 v[2:3], v[4:5], 0, v[114:115]
	v_lshl_add_u64 v[10:11], v[6:7], 0, v[112:113]
	global_load_dwordx4 v[72:75], v[8:9], off
	global_load_dwordx4 v[76:79], v[10:11], off
	v_lshl_add_u64 v[4:5], v[6:7], 0, v[114:115]
	global_load_dwordx4 v[80:83], v[2:3], off
	global_load_dwordx4 v[84:87], v[4:5], off
	v_lshrrev_b32_e32 v3, 1, v0
	v_lshlrev_b32_e32 v4, 1, v0
	v_and_b32_e32 v2, 0x73, v1
	v_and_b32_e32 v3, 4, v3
	v_and_b32_e32 v4, 8, v4
	v_ashrrev_i32_e32 v5, 6, v1
	v_ashrrev_i32_e32 v1, 2, v1
	v_or3_b32 v2, v2, v3, v4
	v_and_b32_e32 v4, 31, v0
	v_and_b32_e32 v10, 0xffffffc0, v1
	v_or_b32_e32 v11, v10, v4
	s_movk_i32 s8, 0x90
	s_add_i32 s3, 0, 0x11800
	v_mul_lo_u32 v11, v11, s8
	v_add_u32_e32 v8, s3, v108
	v_lshl_add_u32 v105, v2, 1, 0
	v_lshlrev_b32_e32 v2, 5, v5
	v_add_u32_e32 v13, 0, v11
	v_add_u32_e32 v11, s3, v11
	s_movk_i32 s3, 0x80
	s_add_i32 s0, 0, 0x16000
	v_and_b32_e32 v9, 0x60, v2
	v_bitop3_b32 v2, v2, s3, v4 bitop3:0x36
	v_lshl_add_u32 v6, v4, 2, s0
	v_lshl_add_u32 v130, v2, 2, s0
	s_movk_i32 s0, 0x880
	v_or_b32_e32 v120, v9, v4
	v_mul_lo_u32 v131, v12, s0
	v_lshrrev_b32_e32 v1, 6, v1
	s_movk_i32 s0, 0x4400
	v_bfe_u32 v3, v0, 5, 1
	v_add_u32_e32 v15, 1, v120
	v_mul_lo_u32 v1, v1, s0
	s_movk_i32 s0, 0x110
	v_lshlrev_b32_e32 v14, 4, v3
	v_cvt_f32_ubyte0_e32 v122, v15
	v_mul_u32_u24_e32 v15, 0x90, v4
	v_mad_u32_u24 v1, v4, s0, v1
	v_add_u32_e32 v7, 0, v108
	v_lshl_add_u64 v[116:117], s[6:7], 0, v[108:109]
	v_lshlrev_b32_e32 v0, 3, v3
	v_sub_u32_e32 v16, 0x80, v120
	v_add3_u32 v121, 0, v15, v14
	v_mul_i32_i24_e32 v15, -4, v3
	v_cmp_eq_u32_e64 s[6:7], 0, v3
	v_lshlrev_b32_e32 v5, 7, v5
	v_lshl_or_b32 v124, v3, 2, v10
	v_mul_lo_u32 v2, v106, s8
	v_add_u32_e32 v3, 0x2200, v131
	v_add3_u32 v1, v1, v14, 0
	v_lshl_add_u64 v[118:119], s[18:19], 0, v[108:109]
	v_cvt_f32_ubyte0_e32 v123, v16
	v_ashrrev_i32_e32 v125, 31, v10
	v_add3_u32 v132, v15, v9, v4
	v_add_u32_e32 v133, 0x4800, v1
	v_add_u32_e32 v134, v7, v2
	v_add_u32_e32 v135, v8, v2
	v_add_u32_e32 v136, v105, v3
	s_mov_b32 s3, 0x3fb8aa3b
	s_mov_b32 s42, 0xc2ce8ed0
	s_mov_b32 s43, 0x42b17218
	v_lshlrev_b32_e32 v108, 1, v0
	v_add_u32_e32 v137, v13, v14
	s_mov_b32 s22, 0xbfb8aa3b
	v_add_u32_e32 v138, v11, v14
	v_add_u32_e32 v139, v6, v5
	v_mov_b32_e32 v140, 0x358637bd
	s_mov_b32 s44, 0x800000
	v_mov_b32_e32 v141, 0x7f800000
	s_mov_b32 s8, s64
	s_waitcnt vmcnt(0)
	s_branch .LBB0_865
.LBB0_864:
	s_or_b64 exec, exec, s[40:41]
	v_lshl_add_u64 v[32:33], v[124:125], 0, s[0:1]
	v_lshl_add_u64 v[32:33], v[32:33], 0, v[126:127]
	v_lshlrev_b64 v[32:33], 1, v[32:33]
	v_lshl_add_u64 v[34:35], s[16:17], 0, v[32:33]
	s_waitcnt lgkmcnt(0)
	s_barrier
	v_mov_b32_e32 v40, v166
	v_mov_b32_e32 v41, v167
	v_mov_b32_e32 v42, v168
	v_mov_b32_e32 v43, v169
	v_mov_b32_e32 v44, v170
	v_mov_b32_e32 v45, v171
	ds_read_b32 v37, v130
	v_mov_b32_e32 v46, v172
	v_mov_b32_e32 v47, v173
	v_mov_b32_e32 v38, v174
	v_mov_b32_e32 v39, v175
	v_mov_b32_e32 v88, v176
	v_mov_b32_e32 v89, v177
	v_lshl_add_u64 v[32:33], s[20:21], 0, v[32:33]
	s_mov_b32 s8, s34
	s_waitcnt lgkmcnt(0)
	v_add_f32_e32 v36, v36, v37
	v_fmamk_f32 v36, v36, 0x3c000000, v140
	v_mul_f32_e32 v37, 0x4b800000, v36
	v_cmp_gt_f32_e32 vcc, s44, v36
	v_lshlrev_b32_e32 v90, 16, v40
	v_cndmask_b32_e32 v36, v36, v37, vcc
	v_rsq_f32_e32 v36, v36
	v_and_b32_e32 v91, 0xffff0000, v40
	v_lshlrev_b32_e32 v40, 16, v41
	v_and_b32_e32 v41, 0xffff0000, v41
	v_mul_f32_e32 v37, 0x45800000, v36
	v_cndmask_b32_e32 v36, v36, v37, vcc
	v_lshlrev_b32_e32 v92, 16, v42
	v_and_b32_e32 v93, 0xffff0000, v42
	v_lshlrev_b32_e32 v42, 16, v43
	v_and_b32_e32 v43, 0xffff0000, v43
	v_mul_f32_e32 v37, 0xbfb8aa3b, v90
	v_mul_f32_e32 v96, 0xbfb8aa3b, v91
	v_mul_f32_e32 v97, 0xbfb8aa3b, v40
	v_mul_f32_e32 v98, 0xbfb8aa3b, v41
	v_lshlrev_b32_e32 v94, 16, v44
	v_mul_f32_e32 v99, 0xbfb8aa3b, v92
	v_mul_f32_e32 v100, 0xbfb8aa3b, v93
	v_mul_f32_e32 v101, 0xbfb8aa3b, v42
	v_mul_f32_e32 v102, 0xbfb8aa3b, v43
	v_exp_f32_e32 v37, v37
	v_exp_f32_e32 v96, v96
	v_exp_f32_e32 v97, v97
	v_exp_f32_e32 v98, v98
	v_mul_f32_e32 v103, 0xbfb8aa3b, v94
	v_exp_f32_e32 v99, v99
	v_exp_f32_e32 v100, v100
	v_exp_f32_e32 v101, v101
	v_exp_f32_e32 v102, v102
	v_and_b32_e32 v95, 0xffff0000, v44
	v_lshlrev_b32_e32 v44, 16, v45
	v_and_b32_e32 v45, 0xffff0000, v45
	v_exp_f32_e32 v103, v103
	v_mul_f32_e32 v128, 0xbfb8aa3b, v45
	v_exp_f32_e32 v129, v128
	v_add_f32_e32 v37, 1.0, v37
	v_add_f32_e32 v128, 1.0, v96
	v_add_f32_e32 v142, 1.0, v97
	v_add_f32_e32 v143, 1.0, v98
	v_add_f32_e32 v144, 1.0, v99
	v_add_f32_e32 v145, 1.0, v100
	v_add_f32_e32 v146, 1.0, v101
	v_add_f32_e32 v147, 1.0, v102
	v_rcp_f32_e32 v96, v37
	v_rcp_f32_e32 v97, v128
	v_rcp_f32_e32 v98, v142
	v_rcp_f32_e32 v99, v143
	v_add_f32_e32 v148, 1.0, v103
	v_rcp_f32_e32 v100, v144
	v_rcp_f32_e32 v101, v145
	v_rcp_f32_e32 v102, v146
	v_rcp_f32_e32 v103, v147
	v_mul_f32_e32 v126, 0xbfb8aa3b, v95
	v_mul_f32_e32 v127, 0xbfb8aa3b, v44
	v_exp_f32_e32 v126, v126
	v_exp_f32_e32 v127, v127
	v_pk_mul_f32 v[90:91], v[96:97], v[90:91]
	v_pk_mul_f32 v[40:41], v[98:99], v[40:41]
	v_pk_mul_f32 v[92:93], v[100:101], v[92:93]
	v_pk_mul_f32 v[42:43], v[102:103], v[42:43]
	v_pk_mul_f32 v[16:17], v[16:17], v[90:91]
	v_pk_mul_f32 v[18:19], v[18:19], v[40:41]
	v_pk_mul_f32 v[20:21], v[20:21], v[92:93]
	v_pk_mul_f32 v[22:23], v[22:23], v[42:43]
	v_pk_mul_f32 v[16:17], v[36:37], v[16:17] op_sel_hi:[0,1]
	v_pk_mul_f32 v[18:19], v[36:37], v[18:19] op_sel_hi:[0,1]
	v_pk_mul_f32 v[20:21], v[36:37], v[20:21] op_sel_hi:[0,1]
	v_pk_mul_f32 v[22:23], v[36:37], v[22:23] op_sel_hi:[0,1]
	v_cvt_pk_bf16_f32 v16, v16, v17
	v_cvt_pk_bf16_f32 v17, v18, v19
	v_add_f32_e32 v149, 1.0, v126
	v_add_f32_e32 v150, 1.0, v127
	v_cvt_pk_bf16_f32 v18, v20, v21
	v_cvt_pk_bf16_f32 v19, v22, v23
	global_store_dwordx2 v[32:33], v[16:17], off
	global_store_dwordx2 v[32:33], v[18:19], off offset:16
	v_add_f32_e32 v16, 1.0, v129
	v_rcp_f32_e32 v126, v148
	v_rcp_f32_e32 v127, v149
	v_rcp_f32_e32 v128, v150
	v_rcp_f32_e32 v129, v16
	v_mov_b32_e32 v20, v178
	v_mov_b32_e32 v21, v179
	v_pk_mul_f32 v[94:95], v[126:127], v[94:95]
	v_lshlrev_b32_e32 v22, 16, v47
	v_pk_mul_f32 v[18:19], v[128:129], v[44:45]
	v_pk_mul_f32 v[16:17], v[24:25], v[94:95]
	v_pk_mul_f32 v[18:19], v[26:27], v[18:19]
	v_pk_mul_f32 v[16:17], v[36:37], v[16:17] op_sel_hi:[0,1]
	v_pk_mul_f32 v[18:19], v[36:37], v[18:19] op_sel_hi:[0,1]
	v_cvt_pk_bf16_f32 v16, v16, v17
	v_cvt_pk_bf16_f32 v17, v18, v19
	global_store_dwordx2 v[32:33], v[16:17], off offset:32
	v_lshlrev_b32_e32 v16, 16, v46
	v_mul_f32_e32 v17, 0xbfb8aa3b, v16
	v_exp_f32_e32 v18, v17
	v_and_b32_e32 v17, 0xffff0000, v46
	v_mul_f32_e32 v19, 0xbfb8aa3b, v17
	v_exp_f32_e32 v19, v19
	v_and_b32_e32 v23, 0xffff0000, v47
	v_add_f32_e32 v18, 1.0, v18
	v_mul_f32_e32 v24, 0xbfb8aa3b, v22
	v_add_f32_e32 v19, 1.0, v19
	v_mul_f32_e32 v25, 0xbfb8aa3b, v23
	v_rcp_f32_e32 v18, v18
	v_rcp_f32_e32 v19, v19
	v_exp_f32_e32 v24, v24
	v_exp_f32_e32 v25, v25
	s_andn2_b64 vcc, exec, s[38:39]
	v_pk_mul_f32 v[16:17], v[18:19], v[16:17]
	v_add_f32_e32 v18, 1.0, v24
	v_add_f32_e32 v19, 1.0, v25
	v_rcp_f32_e32 v18, v18
	v_rcp_f32_e32 v19, v19
	v_pk_mul_f32 v[16:17], v[28:29], v[16:17]
	v_pk_mul_f32 v[18:19], v[18:19], v[22:23]
	s_nop 0
	v_pk_mul_f32 v[18:19], v[30:31], v[18:19]
	v_pk_mul_f32 v[16:17], v[36:37], v[16:17] op_sel_hi:[0,1]
	v_pk_mul_f32 v[18:19], v[36:37], v[18:19] op_sel_hi:[0,1]
	v_cvt_pk_bf16_f32 v16, v16, v17
	v_cvt_pk_bf16_f32 v17, v18, v19
	v_mov_b32_e32 v18, v180
	v_mov_b32_e32 v19, v181
	v_lshlrev_b32_e32 v22, 16, v38
	v_and_b32_e32 v23, 0xffff0000, v38
	v_mul_f32_e32 v24, 0xbfb8aa3b, v22
	v_mul_f32_e32 v25, 0xbfb8aa3b, v23
	v_exp_f32_e32 v24, v24
	v_exp_f32_e32 v25, v25
	global_store_dwordx2 v[32:33], v[16:17], off offset:48
	v_add_f32_e32 v16, 1.0, v24
	v_add_f32_e32 v17, 1.0, v25
	v_lshlrev_b32_e32 v24, 16, v39
	v_and_b32_e32 v25, 0xffff0000, v39
	v_mul_f32_e32 v26, 0xbfb8aa3b, v24
	v_mul_f32_e32 v27, 0xbfb8aa3b, v25
	v_rcp_f32_e32 v16, v16
	v_rcp_f32_e32 v17, v17
	v_exp_f32_e32 v26, v26
	v_exp_f32_e32 v27, v27
	v_pk_mul_f32 v[16:17], v[16:17], v[22:23]
	v_add_f32_e32 v22, 1.0, v26
	v_add_f32_e32 v23, 1.0, v27
	v_rcp_f32_e32 v22, v22
	v_rcp_f32_e32 v23, v23
	v_pk_mul_f32 v[0:1], v[0:1], v[16:17]
	v_pk_mul_f32 v[16:17], v[22:23], v[24:25]
	s_nop 0
	v_pk_mul_f32 v[2:3], v[2:3], v[16:17]
	v_pk_mul_f32 v[0:1], v[36:37], v[0:1] op_sel_hi:[0,1]
	v_pk_mul_f32 v[2:3], v[36:37], v[2:3] op_sel_hi:[0,1]
	v_cvt_pk_bf16_f32 v0, v0, v1
	v_cvt_pk_bf16_f32 v1, v2, v3
	v_lshlrev_b32_e32 v2, 16, v88
	v_and_b32_e32 v3, 0xffff0000, v88
	v_mul_f32_e32 v16, 0xbfb8aa3b, v2
	v_mul_f32_e32 v17, 0xbfb8aa3b, v3
	v_exp_f32_e32 v16, v16
	v_exp_f32_e32 v17, v17
	global_store_dwordx2 v[32:33], v[0:1], off offset:64
	v_add_f32_e32 v0, 1.0, v16
	v_add_f32_e32 v1, 1.0, v17
	v_lshlrev_b32_e32 v16, 16, v89
	v_and_b32_e32 v17, 0xffff0000, v89
	v_mul_f32_e32 v22, 0xbfb8aa3b, v16
	v_mul_f32_e32 v23, 0xbfb8aa3b, v17
	v_rcp_f32_e32 v0, v0
	v_rcp_f32_e32 v1, v1
	v_exp_f32_e32 v22, v22
	v_exp_f32_e32 v23, v23
	v_pk_mul_f32 v[0:1], v[0:1], v[2:3]
	v_add_f32_e32 v2, 1.0, v22
	v_add_f32_e32 v3, 1.0, v23
	v_rcp_f32_e32 v2, v2
	v_rcp_f32_e32 v3, v3
	v_pk_mul_f32 v[0:1], v[4:5], v[0:1]
	v_pk_mul_f32 v[2:3], v[2:3], v[16:17]
	s_nop 0
	v_pk_mul_f32 v[2:3], v[6:7], v[2:3]
	v_pk_mul_f32 v[0:1], v[36:37], v[0:1] op_sel_hi:[0,1]
	v_pk_mul_f32 v[2:3], v[36:37], v[2:3] op_sel_hi:[0,1]
	v_cvt_pk_bf16_f32 v0, v0, v1
	v_cvt_pk_bf16_f32 v1, v2, v3
	v_lshlrev_b32_e32 v2, 16, v20
	v_and_b32_e32 v3, 0xffff0000, v20
	v_mul_f32_e32 v4, 0xbfb8aa3b, v2
	v_mul_f32_e32 v5, 0xbfb8aa3b, v3
	v_exp_f32_e32 v4, v4
	v_exp_f32_e32 v5, v5
	global_store_dwordx2 v[32:33], v[0:1], off offset:80
	v_add_f32_e32 v0, 1.0, v4
	v_add_f32_e32 v1, 1.0, v5
	v_lshlrev_b32_e32 v4, 16, v21
	v_and_b32_e32 v5, 0xffff0000, v21
	v_mul_f32_e32 v6, 0xbfb8aa3b, v4
	v_mul_f32_e32 v7, 0xbfb8aa3b, v5
	v_rcp_f32_e32 v0, v0
	v_rcp_f32_e32 v1, v1
	v_exp_f32_e32 v6, v6
	v_exp_f32_e32 v7, v7
	v_pk_mul_f32 v[0:1], v[0:1], v[2:3]
	v_add_f32_e32 v2, 1.0, v6
	v_add_f32_e32 v3, 1.0, v7
	v_rcp_f32_e32 v2, v2
	v_rcp_f32_e32 v3, v3
	v_pk_mul_f32 v[0:1], v[8:9], v[0:1]
	v_pk_mul_f32 v[2:3], v[2:3], v[4:5]
	s_nop 0
	v_pk_mul_f32 v[2:3], v[10:11], v[2:3]
	v_pk_mul_f32 v[0:1], v[36:37], v[0:1] op_sel_hi:[0,1]
	v_pk_mul_f32 v[2:3], v[36:37], v[2:3] op_sel_hi:[0,1]
	v_cvt_pk_bf16_f32 v0, v0, v1
	v_cvt_pk_bf16_f32 v1, v2, v3
	v_lshlrev_b32_e32 v2, 16, v18
	v_and_b32_e32 v3, 0xffff0000, v18
	v_mul_f32_e32 v4, 0xbfb8aa3b, v2
	v_mul_f32_e32 v5, 0xbfb8aa3b, v3
	v_exp_f32_e32 v4, v4
	v_exp_f32_e32 v5, v5
	global_store_dwordx2 v[32:33], v[0:1], off offset:96
	v_add_f32_e32 v0, 1.0, v4
	v_add_f32_e32 v1, 1.0, v5
	v_lshlrev_b32_e32 v4, 16, v19
	v_and_b32_e32 v5, 0xffff0000, v19
	v_mul_f32_e32 v6, 0xbfb8aa3b, v4
	v_mul_f32_e32 v7, 0xbfb8aa3b, v5
	v_rcp_f32_e32 v0, v0
	v_rcp_f32_e32 v1, v1
	v_exp_f32_e32 v6, v6
	v_exp_f32_e32 v7, v7
	v_pk_mul_f32 v[0:1], v[0:1], v[2:3]
	v_add_f32_e32 v2, 1.0, v6
	v_add_f32_e32 v3, 1.0, v7
	v_rcp_f32_e32 v2, v2
	v_rcp_f32_e32 v3, v3
	v_pk_mul_f32 v[0:1], v[12:13], v[0:1]
	v_pk_mul_f32 v[2:3], v[2:3], v[4:5]
	s_nop 0
	v_pk_mul_f32 v[2:3], v[14:15], v[2:3]
	v_pk_mul_f32 v[0:1], v[36:37], v[0:1] op_sel_hi:[0,1]
	v_pk_mul_f32 v[2:3], v[36:37], v[2:3] op_sel_hi:[0,1]
	v_cvt_pk_bf16_f32 v0, v0, v1
	v_cvt_pk_bf16_f32 v1, v2, v3
	global_store_dwordx2 v[32:33], v[0:1], off offset:112
	s_barrier
	s_cbranch_vccz .LBB0_871
.LBB0_865:
	s_add_i32 s34, s8, s66
	s_cmpk_gt_i32 s34, 0x3ff
	s_cselect_b32 s67, 1, 0
	s_and_b32 s68, s34, 0x60
	s_cselect_b32 s68, 0, 1
	s_cmp_eq_u32 s28, 0x100
	s_cselect_b32 s67, s68, s67
	s_cmp_lg_u32 s67, 0
	s_cselect_b64 s[38:39], -1, 0
	v_add_u32_e32 v0, v105, v131
	s_and_b64 vcc, exec, s[38:39]
	ds_write_b128 v134, v[48:51]
	ds_write_b128 v134, v[72:75] offset:53248
	ds_write_b128 v135, v[76:79]
	ds_write_b128 v134, v[52:55] offset:9216
	ds_write_b128 v134, v[80:83] offset:62464
	ds_write_b128 v135, v[84:87] offset:9216
	ds_write_b16 v0, v56 offset:18432
	ds_write_b16_d16_hi v0, v56 offset:18704
	ds_write_b16 v0, v57 offset:18976
	ds_write_b16_d16_hi v0, v57 offset:19248
	ds_write_b16 v0, v58 offset:19520
	ds_write_b16_d16_hi v0, v58 offset:19792
	ds_write_b16 v0, v59 offset:20064
	ds_write_b16_d16_hi v0, v59 offset:20336
	ds_write_b16 v136, v60 offset:18432
	ds_write_b16_d16_hi v136, v60 offset:18704
	ds_write_b16 v136, v61 offset:18976
	ds_write_b16_d16_hi v136, v61 offset:19248
	ds_write_b16 v136, v62 offset:19520
	ds_write_b16_d16_hi v136, v62 offset:19792
	ds_write_b16 v136, v63 offset:20064
	ds_write_b16_d16_hi v136, v63 offset:20336
	ds_write_b16 v136, v64 offset:27136
	ds_write_b16_d16_hi v136, v64 offset:27408
	ds_write_b16 v136, v65 offset:27680
	ds_write_b16_d16_hi v136, v65 offset:27952
	ds_write_b16 v136, v66 offset:28224
	ds_write_b16_d16_hi v136, v66 offset:28496
	ds_write_b16 v136, v67 offset:28768
	ds_write_b16_d16_hi v136, v67 offset:29040
	ds_write_b16 v136, v68 offset:35840
	ds_write_b16_d16_hi v136, v68 offset:36112
	ds_write_b16 v136, v69 offset:36384
	ds_write_b16_d16_hi v136, v69 offset:36656
	ds_write_b16 v136, v70 offset:36928
	ds_write_b16_d16_hi v136, v70 offset:37200
	ds_write_b16 v136, v71 offset:37472
	ds_write_b16_d16_hi v136, v71 offset:37744
	s_waitcnt lgkmcnt(0)
	s_barrier
	s_cbranch_vccnz .LBB0_867
	s_ashr_i32 s40, s34, 9
	s_and_b32 s0, s34, 63
	s_ashr_i32 s41, s40, 31
	s_lshl_b64 s[40:41], s[40:41], 13
	s_lshl_b32 s0, s0, 7
	s_bfe_u32 s9, s34, 0x30006
	s_or_b32 s40, s40, s0
	v_lshl_add_u64 v[0:1], s[40:41], 0, v[106:107]
	s_lshl_b32 s0, s9, 7
	v_lshl_add_u64 v[2:3], v[116:117], 0, s[0:1]
	v_lshlrev_b64 v[0:1], 10, v[0:1]
	v_lshl_add_u64 v[0:1], v[2:3], 0, v[0:1]
	v_add_co_u32_e32 v2, vcc, s23, v0
	s_lshl_b32 s0, s9, 8
	s_nop 0
	v_addc_co_u32_e32 v3, vcc, 0, v1, vcc
	global_load_dwordx4 v[48:51], v[0:1], off
	global_load_dwordx4 v[52:55], v[2:3], off
	v_mov_b32_e32 v1, s41
	v_or_b32_e32 v0, s40, v104
	v_lshlrev_b64 v[0:1], 11, v[0:1]
	v_lshl_add_u64 v[0:1], s[12:13], 0, v[0:1]
	v_lshl_add_u64 v[0:1], v[0:1], 0, s[0:1]
	s_ashr_i32 s35, s34, 31
	s_add_i32 s46, s34, 0x400
	v_lshl_add_u64 v[0:1], v[110:111], 1, v[0:1]
	s_lshl_b64 s[40:41], s[34:35], 14
	s_ashr_i32 s47, s46, 31
	global_load_dwordx4 v[56:59], v[0:1], off
	global_load_dwordx4 v[60:63], v[0:1], off offset:64
	global_load_dwordx4 v[64:67], v[0:1], off offset:128
	global_load_dwordx4 v[68:71], v[0:1], off offset:192
	s_lshl_b64 s[46:47], s[46:47], 14
	v_lshl_add_u64 v[0:1], v[118:119], 0, s[40:41]
	v_lshl_add_u64 v[2:3], v[118:119], 0, s[46:47]
	v_lshl_add_u64 v[4:5], v[0:1], 0, v[112:113]
	v_lshl_add_u64 v[0:1], v[0:1], 0, v[114:115]
	v_lshl_add_u64 v[6:7], v[2:3], 0, v[112:113]
	global_load_dwordx4 v[72:75], v[4:5], off
	global_load_dwordx4 v[76:79], v[6:7], off
	v_lshl_add_u64 v[2:3], v[2:3], 0, v[114:115]
	global_load_dwordx4 v[80:83], v[0:1], off
	global_load_dwordx4 v[84:87], v[2:3], off
.LBB0_867:
	s_ashr_i32 s40, s8, 9
	s_ashr_i32 s41, s40, 31
	s_lshl_b32 s0, s8, 7
	s_and_b32 s0, s0, 0x1f80
	s_lshl_b64 s[40:41], s[40:41], 13
	s_or_b32 s0, s40, s0
	v_mov_b32_e32 v1, s41
	v_or_b32_e32 v0, s0, v120
	s_bfe_u32 s8, s8, 0x30006
	v_lshlrev_b64 v[126:127], 10, v[0:1]
	v_lshl_add_u64 v[0:1], s[10:11], 0, v[126:127]
	s_lshl_b32 s0, s8, 7
	v_lshl_add_u64 v[0:1], v[0:1], 0, s[0:1]
	v_lshl_add_u64 v[40:41], v[0:1], 0, v[108:109]
	v_lshl_add_u64 v[164:165], v[124:125], 0, s[0:1]
	v_lshl_add_u64 v[164:165], v[164:165], 0, v[126:127]
	v_lshlrev_b64 v[164:165], 1, v[164:165]
	v_lshl_add_u64 v[164:165], s[16:17], 0, v[164:165]
	global_load_dwordx2 v[166:167], v[164:165], off
	global_load_dwordx2 v[168:169], v[164:165], off offset:16
	global_load_dwordx2 v[170:171], v[164:165], off offset:32
	global_load_dwordx2 v[172:173], v[164:165], off offset:48
	global_load_dwordx2 v[174:175], v[164:165], off offset:64
	global_load_dwordx2 v[176:177], v[164:165], off offset:80
	global_load_dwordx2 v[178:179], v[164:165], off offset:96
	global_load_dwordx2 v[180:181], v[164:165], off offset:112
	global_load_dwordx4 v[88:91], v[40:41], off
	global_load_dwordx4 v[92:95], v[40:41], off offset:32
	s_lshl_b32 s8, s8, 2
	v_mov_b32_e32 v0, s8
	global_load_dword v128, v0, s[50:51]
	global_load_dword v129, v0, s[52:53]
	global_load_dwordx4 v[96:99], v[40:41], off offset:64
	ds_read_b128 v[0:3], v137 offset:53248
	ds_read_b128 v[32:35], v137 offset:53280
	ds_read_b128 v[16:19], v137 offset:57856
	ds_read_b128 v[36:39], v137 offset:57888
	global_load_dwordx4 v[100:103], v[40:41], off offset:96
	ds_read_b128 v[40:43], v137 offset:53312
	ds_read_b128 v[44:47], v137 offset:53344
	s_mov_b32 s35, 0
	s_waitcnt vmcnt(5) lgkmcnt(5)
	v_mfma_f32_32x32x16_bf16 v[0:15], v[0:3], v[88:91], 0
	s_waitcnt vmcnt(3)
	v_mul_f32_e32 v146, 0x3fb8aa3b, v128
	s_waitcnt vmcnt(2)
	v_mul_f32_e32 v147, 0x3fb8aa3b, v129
	v_fma_f32 v148, v128, s3, -v146
	v_rndne_f32_e32 v149, v146
	v_fma_f32 v150, v129, s3, -v147
	s_waitcnt lgkmcnt(3)
	v_mfma_f32_32x32x16_bf16 v[16:31], v[16:19], v[88:91], 0
	v_fmac_f32_e32 v148, 0x32a5705f, v128
	v_fmac_f32_e32 v150, 0x32a5705f, v129
	v_cmp_ngt_f32_e32 vcc, s42, v128
	v_mfma_f32_32x32x16_bf16 v[0:15], v[32:35], v[92:95], v[0:15]
	ds_read_b128 v[32:35], v137 offset:57920
	ds_read_b128 v[142:145], v137 offset:57952
	s_waitcnt lgkmcnt(4)
	v_mfma_f32_32x32x16_bf16 v[16:31], v[36:39], v[92:95], v[16:31]
	v_rndne_f32_e32 v36, v147
	v_sub_f32_e32 v37, v146, v149
	v_sub_f32_e32 v39, v147, v36
	v_add_f32_e32 v37, v37, v148
	v_cvt_i32_f32_e32 v38, v149
	v_add_f32_e32 v39, v39, v150
	v_exp_f32_e32 v37, v37
	s_waitcnt vmcnt(1) lgkmcnt(3)
	v_mfma_f32_32x32x16_bf16 v[0:15], v[40:43], v[96:99], v[0:15]
	v_cvt_i32_f32_e32 v36, v36
	v_exp_f32_e32 v39, v39
	v_ldexp_f32 v37, v37, v38
	ds_read_b128 v[146:149], v138
	ds_read_b128 v[150:153], v138 offset:32
	ds_read_b128 v[154:157], v138 offset:4608
	ds_read_b128 v[158:161], v138 offset:4640
	s_waitcnt lgkmcnt(5)
	v_mfma_f32_32x32x16_bf16 v[16:31], v[32:35], v[96:99], v[16:31]
	v_ldexp_f32 v32, v39, v36
	v_cndmask_b32_e32 v33, 0, v37, vcc
	v_cmp_ngt_f32_e32 vcc, s42, v129
	s_nop 1
	v_cndmask_b32_e32 v34, 0, v32, vcc
	v_cmp_nlt_f32_e32 vcc, s43, v128
	s_waitcnt vmcnt(0)
	v_mfma_f32_32x32x16_bf16 v[0:15], v[44:47], v[100:103], v[0:15]
	v_cndmask_b32_e32 v32, v141, v33, vcc
	v_cmp_nlt_f32_e32 vcc, s43, v129
	s_nop 1
	v_cndmask_b32_e32 v33, v141, v34, vcc
	v_mul_f32_e64 v128, v32, s22
	v_mul_f32_e64 v129, v33, s22
	s_waitcnt lgkmcnt(4)
	v_mfma_f32_32x32x16_bf16 v[16:31], v[142:145], v[100:103], v[16:31]
	v_mul_f32_e64 v162, v128, v122
	v_mul_f32_e64 v163, v129, v123
	v_mov_b32_e32 v142, v121
	v_sub_f32_e32 v32, v162, v163
	v_exp_f32_e32 v162, v32
	v_mov_b32_e32 v143, v133
	v_pk_mul_f32 v[32:33], v[162:163], v[0:1] op_sel_hi:[0,1]
	v_pk_mul_f32 v[46:47], v[162:163], v[14:15] op_sel_hi:[0,1]
	v_pk_mul_f32 v[44:45], v[162:163], v[12:13] op_sel_hi:[0,1]
	v_pk_mul_f32 v[42:43], v[162:163], v[10:11] op_sel_hi:[0,1]
	v_pk_mul_f32 v[40:41], v[162:163], v[8:9] op_sel_hi:[0,1]
	v_pk_mul_f32 v[38:39], v[162:163], v[6:7] op_sel_hi:[0,1]
	v_pk_mul_f32 v[36:37], v[162:163], v[4:5] op_sel_hi:[0,1]
	v_pk_mul_f32 v[34:35], v[162:163], v[2:3] op_sel_hi:[0,1]
	v_pk_mul_f32 v[0:1], v[162:163], v[16:17] op_sel_hi:[0,1]
	v_pk_mul_f32 v[14:15], v[162:163], v[30:31] op_sel_hi:[0,1]
	s_waitcnt lgkmcnt(3)
	v_mfma_f32_32x32x16_bf16 v[32:47], v[146:149], v[88:91], v[32:47]
	v_mul_f32_e64 v12, v162, v28
	v_mul_f32_e64 v13, v162, v29
	v_mul_f32_e64 v10, v162, v26
	v_mul_f32_e64 v11, v162, v27
	v_mul_f32_e64 v8, v162, v24
	v_mul_f32_e64 v9, v162, v25
	v_pk_mul_f32 v[6:7], v[162:163], v[22:23] op_sel_hi:[0,1]
	v_pk_mul_f32 v[4:5], v[162:163], v[20:21] op_sel_hi:[0,1]
	v_pk_mul_f32 v[2:3], v[162:163], v[18:19] op_sel_hi:[0,1]
	ds_read_b128 v[16:19], v138 offset:64
	ds_read_b128 v[20:23], v138 offset:96
	s_waitcnt lgkmcnt(3)
	v_mfma_f32_32x32x16_bf16 v[0:15], v[154:157], v[88:91], v[0:15]
	v_mfma_f32_32x32x16_bf16 v[32:47], v[150:153], v[92:95], v[32:47]
	s_waitcnt lgkmcnt(2)
	v_mfma_f32_32x32x16_bf16 v[0:15], v[158:161], v[92:95], v[0:15]
	s_waitcnt lgkmcnt(1)
	v_mfma_f32_32x32x16_bf16 v[32:47], v[16:19], v[96:99], v[32:47]
	ds_read_b128 v[16:19], v138 offset:4672
	ds_read_b128 v[24:27], v138 offset:4704
	s_waitcnt lgkmcnt(1)
	v_mfma_f32_32x32x16_bf16 v[0:15], v[16:19], v[96:99], v[0:15]
	v_exp_f32_e32 v16, v163
	v_mfma_f32_32x32x16_bf16 v[32:47], v[20:23], v[100:103], v[32:47]
	s_waitcnt lgkmcnt(0)
	v_mfma_f32_32x32x16_bf16 v[0:15], v[24:27], v[100:103], v[0:15]
	s_nop 9
	v_mul_f32_e64 v30, v16, v46
	v_mul_f32_e64 v31, v16, v47
	v_mul_f32_e64 v28, v16, v44
	v_mul_f32_e64 v29, v16, v45
	v_mul_f32_e64 v26, v16, v42
	v_mul_f32_e64 v27, v16, v43
	v_pk_mul_f32 v[24:25], v[16:17], v[40:41] op_sel_hi:[0,1]
	v_pk_mul_f32 v[22:23], v[16:17], v[38:39] op_sel_hi:[0,1]
	v_pk_mul_f32 v[20:21], v[16:17], v[36:37] op_sel_hi:[0,1]
	v_pk_mul_f32 v[18:19], v[16:17], v[34:35] op_sel_hi:[0,1]
	v_pk_mul_f32 v[14:15], v[16:17], v[14:15] op_sel_hi:[0,1]
	v_pk_mul_f32 v[12:13], v[16:17], v[12:13] op_sel_hi:[0,1]
	v_pk_mul_f32 v[10:11], v[16:17], v[10:11] op_sel_hi:[0,1]
	v_pk_mul_f32 v[8:9], v[16:17], v[8:9] op_sel_hi:[0,1]
	v_pk_mul_f32 v[6:7], v[16:17], v[6:7] op_sel_hi:[0,1]
	v_pk_mul_f32 v[4:5], v[16:17], v[4:5] op_sel_hi:[0,1]
	v_pk_mul_f32 v[2:3], v[16:17], v[2:3] op_sel_hi:[0,1]
	v_pk_mul_f32 v[0:1], v[16:17], v[0:1] op_sel_hi:[0,1]
	v_pk_mul_f32 v[16:17], v[16:17], v[32:33] op_sel_hi:[0,1]

.LBB0_1237:
	v_lshl_add_u32 v148, s38, 8, v150
	v_lshl_or_b32 v146, s8, 7, v152
	v_ashrrev_i32_e32 v147, 31, v146
	v_lshlrev_b64 v[146:147], 1, v[146:147]
	v_mov_b64_e32 v[144:145], s[12:13]
	v_mov_b32_e32 v149, v148
	v_lshlrev_b32_e32 v157, 6, v149
	global_load_dwordx4 v[178:181], v157, s[14:15]
	global_load_dwordx4 v[182:185], v157, s[14:15] offset:16
	global_load_dwordx4 v[186:189], v157, s[14:15] offset:32
	global_load_dwordx4 v[190:193], v157, s[14:15] offset:48
	v_or_b32_e32 v149, 16, v148
	v_lshlrev_b32_e32 v157, 6, v149
	global_load_dwordx4 v[194:197], v157, s[14:15]
	global_load_dwordx4 v[198:201], v157, s[14:15] offset:16
	global_load_dwordx4 v[202:205], v157, s[14:15] offset:32
	global_load_dwordx4 v[206:209], v157, s[14:15] offset:48
	v_or_b32_e32 v149, 32, v148
	v_lshlrev_b32_e32 v157, 6, v149
	global_load_dwordx4 v[210:213], v157, s[14:15]
	global_load_dwordx4 v[214:217], v157, s[14:15] offset:16
	global_load_dwordx4 v[218:221], v157, s[14:15] offset:32
	global_load_dwordx4 v[222:225], v157, s[14:15] offset:48
	v_or_b32_e32 v149, 48, v148
	v_lshlrev_b32_e32 v157, 6, v149
	global_load_dwordx4 v[226:229], v157, s[14:15]
	global_load_dwordx4 v[230:233], v157, s[14:15] offset:16
	global_load_dwordx4 v[234:237], v157, s[14:15] offset:32
	global_load_dwordx4 v[238:241], v157, s[14:15] offset:48
	s_waitcnt vmcnt(0)
	v_pk_add_f32 v[180:181], v[180:181], v[184:185]
	v_pk_add_f32 v[178:179], v[178:179], v[182:183]
	v_pk_add_f32 v[182:183], v[188:189], v[192:193]
	v_pk_add_f32 v[184:185], v[186:187], v[190:191]
	v_pk_add_f32 v[180:181], v[180:181], v[182:183]
	v_pk_add_f32 v[178:179], v[178:179], v[184:185]
	s_nop 0
	v_pk_mov_b32 v[182:183], v[178:179], v[180:181] op_sel:[1,0]
	v_mov_b32_e32 v179, v181
	v_pk_add_f32 v[178:179], v[182:183], v[178:179]
	s_nop 0
	v_add_f32_e32 v178, v178, v179
	v_fmamk_f32 v178, v178, 0x3a800000, v156
	v_mul_f32_e32 v179, 0x4b800000, v178
	v_cmp_gt_f32_e32 vcc, s60, v178
	s_nop 1
	v_cndmask_b32_e32 v178, v178, v179, vcc
	v_rsq_f32_e32 v180, v178
	s_nop 0
	v_mul_f32_e32 v181, 0x45800000, v180
	v_cndmask_b32_e32 v242, v180, v181, vcc
	v_pk_add_f32 v[196:197], v[196:197], v[200:201]
	v_pk_add_f32 v[194:195], v[194:195], v[198:199]
	v_pk_add_f32 v[198:199], v[204:205], v[208:209]
	v_pk_add_f32 v[200:201], v[202:203], v[206:207]
	v_pk_add_f32 v[196:197], v[196:197], v[198:199]
	v_pk_add_f32 v[194:195], v[194:195], v[200:201]
	s_nop 0
	v_pk_mov_b32 v[198:199], v[194:195], v[196:197] op_sel:[1,0]
	v_mov_b32_e32 v195, v197
	v_pk_add_f32 v[194:195], v[198:199], v[194:195]
	s_nop 0
	v_add_f32_e32 v194, v194, v195
	v_fmamk_f32 v194, v194, 0x3a800000, v156
	v_mul_f32_e32 v195, 0x4b800000, v194
	v_cmp_gt_f32_e32 vcc, s60, v194
	s_nop 1
	v_cndmask_b32_e32 v194, v194, v195, vcc
	v_rsq_f32_e32 v196, v194
	s_nop 0
	v_mul_f32_e32 v197, 0x45800000, v196
	v_cndmask_b32_e32 v243, v196, v197, vcc
	v_pk_add_f32 v[212:213], v[212:213], v[216:217]
	v_pk_add_f32 v[210:211], v[210:211], v[214:215]
	v_pk_add_f32 v[214:215], v[220:221], v[224:225]
	v_pk_add_f32 v[216:217], v[218:219], v[222:223]
	v_pk_add_f32 v[212:213], v[212:213], v[214:215]
	v_pk_add_f32 v[210:211], v[210:211], v[216:217]
	s_nop 0
	v_pk_mov_b32 v[214:215], v[210:211], v[212:213] op_sel:[1,0]
	v_mov_b32_e32 v211, v213
	v_pk_add_f32 v[210:211], v[214:215], v[210:211]
	s_nop 0
	v_add_f32_e32 v210, v210, v211
	v_fmamk_f32 v210, v210, 0x3a800000, v156
	v_mul_f32_e32 v211, 0x4b800000, v210
	v_cmp_gt_f32_e32 vcc, s60, v210
	s_nop 1
	v_cndmask_b32_e32 v210, v210, v211, vcc
	v_rsq_f32_e32 v212, v210
	s_nop 0
	v_mul_f32_e32 v213, 0x45800000, v212
	v_cndmask_b32_e32 v244, v212, v213, vcc
	v_pk_add_f32 v[228:229], v[228:229], v[232:233]
	v_pk_add_f32 v[226:227], v[226:227], v[230:231]
	v_pk_add_f32 v[230:231], v[236:237], v[240:241]
	v_pk_add_f32 v[232:233], v[234:235], v[238:239]
	v_pk_add_f32 v[228:229], v[228:229], v[230:231]
	v_pk_add_f32 v[226:227], v[226:227], v[232:233]
	s_nop 0
	v_pk_mov_b32 v[230:231], v[226:227], v[228:229] op_sel:[1,0]
	v_mov_b32_e32 v227, v229
	v_pk_add_f32 v[226:227], v[230:231], v[226:227]
	s_nop 0
	v_add_f32_e32 v226, v226, v227
	v_fmamk_f32 v226, v226, 0x3a800000, v156
	v_mul_f32_e32 v227, 0x4b800000, v226
	v_cmp_gt_f32_e32 vcc, s60, v226
	s_nop 1
	v_cndmask_b32_e32 v226, v226, v227, vcc
	v_rsq_f32_e32 v228, v226
	s_nop 0
	v_mul_f32_e32 v229, 0x45800000, v228
	v_cndmask_b32_e32 v245, v228, v229, vcc
	v_or_b32_e32 v149, 0x80, v148
	v_lshlrev_b32_e32 v157, 6, v149
	global_load_dwordx4 v[178:181], v157, s[14:15]
	global_load_dwordx4 v[182:185], v157, s[14:15] offset:16
	global_load_dwordx4 v[186:189], v157, s[14:15] offset:32
	global_load_dwordx4 v[190:193], v157, s[14:15] offset:48
	v_or_b32_e32 v149, 0x90, v148
	v_lshlrev_b32_e32 v157, 6, v149
	global_load_dwordx4 v[194:197], v157, s[14:15]
	global_load_dwordx4 v[198:201], v157, s[14:15] offset:16
	global_load_dwordx4 v[202:205], v157, s[14:15] offset:32
	global_load_dwordx4 v[206:209], v157, s[14:15] offset:48
	v_or_b32_e32 v149, 0xa0, v148
	v_lshlrev_b32_e32 v157, 6, v149
	global_load_dwordx4 v[210:213], v157, s[14:15]
	global_load_dwordx4 v[214:217], v157, s[14:15] offset:16
	global_load_dwordx4 v[218:221], v157, s[14:15] offset:32
	global_load_dwordx4 v[222:225], v157, s[14:15] offset:48
	v_or_b32_e32 v149, 0xb0, v148
	v_lshlrev_b32_e32 v157, 6, v149
	global_load_dwordx4 v[226:229], v157, s[14:15]
	global_load_dwordx4 v[230:233], v157, s[14:15] offset:16
	global_load_dwordx4 v[234:237], v157, s[14:15] offset:32
	global_load_dwordx4 v[238:241], v157, s[14:15] offset:48
	v_mov_b32_e32 v149, v148
	v_mad_i64_i32 v[158:159], s[8:9], v149, s61, v[144:145]
	v_lshl_add_u64 v[158:159], v[158:159], 0, v[146:147]
	v_mov_b32_e32 v168, v242
	v_pk_mul_f32 v[124:125], v[124:125], v[168:169] op_sel_hi:[1,0]
	v_pk_mul_f32 v[126:127], v[126:127], v[168:169] op_sel_hi:[1,0]
	v_pk_mul_f32 v[120:121], v[120:121], v[168:169] op_sel_hi:[1,0]
	v_pk_mul_f32 v[122:123], v[122:123], v[168:169] op_sel_hi:[1,0]
	v_pk_mul_f32 v[116:117], v[116:117], v[168:169] op_sel_hi:[1,0]
	v_pk_mul_f32 v[118:119], v[118:119], v[168:169] op_sel_hi:[1,0]
	v_pk_mul_f32 v[112:113], v[112:113], v[168:169] op_sel_hi:[1,0]
	v_pk_mul_f32 v[114:115], v[114:115], v[168:169] op_sel_hi:[1,0]
	v_mul_f32_e32 v160, 0xbfb8aa3b, v124
	v_mul_f32_e32 v161, 0xbfb8aa3b, v125
	v_mul_f32_e32 v162, 0xbfb8aa3b, v126
	v_mul_f32_e32 v163, 0xbfb8aa3b, v127
	v_mul_f32_e32 v164, 0xbfb8aa3b, v120
	v_mul_f32_e32 v165, 0xbfb8aa3b, v121
	v_mul_f32_e32 v166, 0xbfb8aa3b, v122
	v_mul_f32_e32 v167, 0xbfb8aa3b, v123
	v_exp_f32_e32 v160, v160
	v_exp_f32_e32 v161, v161
	v_exp_f32_e32 v162, v162
	v_exp_f32_e32 v163, v163
	v_exp_f32_e32 v164, v164
	v_exp_f32_e32 v165, v165
	v_exp_f32_e32 v166, v166
	v_exp_f32_e32 v167, v167
	v_add_f32_e32 v160, 1.0, v160
	v_add_f32_e32 v161, 1.0, v161
	v_add_f32_e32 v162, 1.0, v162
	v_add_f32_e32 v163, 1.0, v163
	v_add_f32_e32 v164, 1.0, v164
	v_add_f32_e32 v165, 1.0, v165
	v_add_f32_e32 v166, 1.0, v166
	v_add_f32_e32 v167, 1.0, v167
	v_rcp_f32_e32 v160, v160
	v_rcp_f32_e32 v161, v161
	v_rcp_f32_e32 v162, v162
	v_rcp_f32_e32 v163, v163
	v_rcp_f32_e32 v164, v164
	v_rcp_f32_e32 v165, v165
	v_rcp_f32_e32 v166, v166
	v_rcp_f32_e32 v167, v167
	v_pk_mul_f32 v[124:125], v[124:125], v[160:161]
	v_pk_mul_f32 v[126:127], v[126:127], v[162:163]
	v_pk_mul_f32 v[120:121], v[120:121], v[164:165]
	v_pk_mul_f32 v[122:123], v[122:123], v[166:167]
	v_pk_mul_f32 v[116:117], v[116:117], v[124:125]
	v_pk_mul_f32 v[118:119], v[118:119], v[126:127]
	v_pk_mul_f32 v[120:121], v[112:113], v[120:121]
	v_pk_mul_f32 v[122:123], v[114:115], v[122:123]
	v_cvt_pk_bf16_f32 v112, v116, v117
	v_cvt_pk_bf16_f32 v113, v118, v119
	v_cvt_pk_bf16_f32 v114, v120, v121
	v_cvt_pk_bf16_f32 v115, v122, v123
	global_store_dwordx4 v[158:159], v[112:115], off nt
	v_or_b32_e32 v149, 16, v148
	v_mad_i64_i32 v[158:159], s[8:9], v149, s61, v[144:145]
	v_lshl_add_u64 v[158:159], v[158:159], 0, v[146:147]
	v_mov_b32_e32 v168, v243
	v_pk_mul_f32 v[108:109], v[108:109], v[168:169] op_sel_hi:[1,0]
	v_pk_mul_f32 v[110:111], v[110:111], v[168:169] op_sel_hi:[1,0]
	v_pk_mul_f32 v[104:105], v[104:105], v[168:169] op_sel_hi:[1,0]
	v_pk_mul_f32 v[106:107], v[106:107], v[168:169] op_sel_hi:[1,0]
	v_pk_mul_f32 v[100:101], v[100:101], v[168:169] op_sel_hi:[1,0]
	v_pk_mul_f32 v[102:103], v[102:103], v[168:169] op_sel_hi:[1,0]
	v_pk_mul_f32 v[96:97], v[96:97], v[168:169] op_sel_hi:[1,0]
	v_pk_mul_f32 v[98:99], v[98:99], v[168:169] op_sel_hi:[1,0]
	v_mul_f32_e32 v160, 0xbfb8aa3b, v108
	v_mul_f32_e32 v161, 0xbfb8aa3b, v109
	v_mul_f32_e32 v162, 0xbfb8aa3b, v110
	v_mul_f32_e32 v163, 0xbfb8aa3b, v111
	v_mul_f32_e32 v164, 0xbfb8aa3b, v104
	v_mul_f32_e32 v165, 0xbfb8aa3b, v105
	v_mul_f32_e32 v166, 0xbfb8aa3b, v106
	v_mul_f32_e32 v167, 0xbfb8aa3b, v107
	v_exp_f32_e32 v160, v160
	v_exp_f32_e32 v161, v161
	v_exp_f32_e32 v162, v162
	v_exp_f32_e32 v163, v163
	v_exp_f32_e32 v164, v164
	v_exp_f32_e32 v165, v165
	v_exp_f32_e32 v166, v166
	v_exp_f32_e32 v167, v167
	v_add_f32_e32 v160, 1.0, v160
	v_add_f32_e32 v161, 1.0, v161
	v_add_f32_e32 v162, 1.0, v162
	v_add_f32_e32 v163, 1.0, v163
	v_add_f32_e32 v164, 1.0, v164
	v_add_f32_e32 v165, 1.0, v165
	v_add_f32_e32 v166, 1.0, v166
	v_add_f32_e32 v167, 1.0, v167
	v_rcp_f32_e32 v160, v160
	v_rcp_f32_e32 v161, v161
	v_rcp_f32_e32 v162, v162
	v_rcp_f32_e32 v163, v163
	v_rcp_f32_e32 v164, v164
	v_rcp_f32_e32 v165, v165
	v_rcp_f32_e32 v166, v166
	v_rcp_f32_e32 v167, v167
	v_pk_mul_f32 v[108:109], v[108:109], v[160:161]
	v_pk_mul_f32 v[110:111], v[110:111], v[162:163]
	v_pk_mul_f32 v[104:105], v[104:105], v[164:165]
	v_pk_mul_f32 v[106:107], v[106:107], v[166:167]
	v_pk_mul_f32 v[100:101], v[100:101], v[108:109]
	v_pk_mul_f32 v[102:103], v[102:103], v[110:111]
	v_pk_mul_f32 v[104:105], v[96:97], v[104:105]
	v_pk_mul_f32 v[106:107], v[98:99], v[106:107]
	v_cvt_pk_bf16_f32 v96, v100, v101
	v_cvt_pk_bf16_f32 v97, v102, v103
	v_cvt_pk_bf16_f32 v98, v104, v105
	v_cvt_pk_bf16_f32 v99, v106, v107
	global_store_dwordx4 v[158:159], v[96:99], off nt
	v_or_b32_e32 v149, 32, v148
	v_mad_i64_i32 v[158:159], s[8:9], v149, s61, v[144:145]
	v_lshl_add_u64 v[158:159], v[158:159], 0, v[146:147]
	v_mov_b32_e32 v168, v244
	v_pk_mul_f32 v[92:93], v[92:93], v[168:169] op_sel_hi:[1,0]
	v_pk_mul_f32 v[94:95], v[94:95], v[168:169] op_sel_hi:[1,0]
	v_pk_mul_f32 v[88:89], v[88:89], v[168:169] op_sel_hi:[1,0]
	v_pk_mul_f32 v[90:91], v[90:91], v[168:169] op_sel_hi:[1,0]
	v_pk_mul_f32 v[84:85], v[84:85], v[168:169] op_sel_hi:[1,0]
	v_pk_mul_f32 v[86:87], v[86:87], v[168:169] op_sel_hi:[1,0]
	v_pk_mul_f32 v[80:81], v[80:81], v[168:169] op_sel_hi:[1,0]
	v_pk_mul_f32 v[82:83], v[82:83], v[168:169] op_sel_hi:[1,0]
	v_mul_f32_e32 v160, 0xbfb8aa3b, v92
	v_mul_f32_e32 v161, 0xbfb8aa3b, v93
	v_mul_f32_e32 v162, 0xbfb8aa3b, v94
	v_mul_f32_e32 v163, 0xbfb8aa3b, v95
	v_mul_f32_e32 v164, 0xbfb8aa3b, v88
	v_mul_f32_e32 v165, 0xbfb8aa3b, v89
	v_mul_f32_e32 v166, 0xbfb8aa3b, v90
	v_mul_f32_e32 v167, 0xbfb8aa3b, v91
	v_exp_f32_e32 v160, v160
	v_exp_f32_e32 v161, v161
	v_exp_f32_e32 v162, v162
	v_exp_f32_e32 v163, v163
	v_exp_f32_e32 v164, v164
	v_exp_f32_e32 v165, v165
	v_exp_f32_e32 v166, v166
	v_exp_f32_e32 v167, v167
	v_add_f32_e32 v160, 1.0, v160
	v_add_f32_e32 v161, 1.0, v161
	v_add_f32_e32 v162, 1.0, v162
	v_add_f32_e32 v163, 1.0, v163
	v_add_f32_e32 v164, 1.0, v164
	v_add_f32_e32 v165, 1.0, v165
	v_add_f32_e32 v166, 1.0, v166
	v_add_f32_e32 v167, 1.0, v167
	v_rcp_f32_e32 v160, v160
	v_rcp_f32_e32 v161, v161
	v_rcp_f32_e32 v162, v162
	v_rcp_f32_e32 v163, v163
	v_rcp_f32_e32 v164, v164
	v_rcp_f32_e32 v165, v165
	v_rcp_f32_e32 v166, v166
	v_rcp_f32_e32 v167, v167
	v_pk_mul_f32 v[92:93], v[92:93], v[160:161]
	v_pk_mul_f32 v[94:95], v[94:95], v[162:163]
	v_pk_mul_f32 v[88:89], v[88:89], v[164:165]
	v_pk_mul_f32 v[90:91], v[90:91], v[166:167]
	v_pk_mul_f32 v[84:85], v[84:85], v[92:93]
	v_pk_mul_f32 v[86:87], v[86:87], v[94:95]
	v_pk_mul_f32 v[88:89], v[80:81], v[88:89]
	v_pk_mul_f32 v[90:91], v[82:83], v[90:91]
	v_cvt_pk_bf16_f32 v80, v84, v85
	v_cvt_pk_bf16_f32 v81, v86, v87
	v_cvt_pk_bf16_f32 v82, v88, v89
	v_cvt_pk_bf16_f32 v83, v90, v91
	global_store_dwordx4 v[158:159], v[80:83], off nt
	v_or_b32_e32 v149, 48, v148
	v_mad_i64_i32 v[158:159], s[8:9], v149, s61, v[144:145]
	v_lshl_add_u64 v[158:159], v[158:159], 0, v[146:147]
	v_mov_b32_e32 v168, v245
	v_pk_mul_f32 v[76:77], v[76:77], v[168:169] op_sel_hi:[1,0]
	v_pk_mul_f32 v[78:79], v[78:79], v[168:169] op_sel_hi:[1,0]
	v_pk_mul_f32 v[72:73], v[72:73], v[168:169] op_sel_hi:[1,0]
	v_pk_mul_f32 v[74:75], v[74:75], v[168:169] op_sel_hi:[1,0]
	v_pk_mul_f32 v[68:69], v[68:69], v[168:169] op_sel_hi:[1,0]
	v_pk_mul_f32 v[70:71], v[70:71], v[168:169] op_sel_hi:[1,0]
	v_pk_mul_f32 v[64:65], v[64:65], v[168:169] op_sel_hi:[1,0]
	v_pk_mul_f32 v[66:67], v[66:67], v[168:169] op_sel_hi:[1,0]
	v_mul_f32_e32 v160, 0xbfb8aa3b, v76
	v_mul_f32_e32 v161, 0xbfb8aa3b, v77
	v_mul_f32_e32 v162, 0xbfb8aa3b, v78
	v_mul_f32_e32 v163, 0xbfb8aa3b, v79
	v_mul_f32_e32 v164, 0xbfb8aa3b, v72
	v_mul_f32_e32 v165, 0xbfb8aa3b, v73
	v_mul_f32_e32 v166, 0xbfb8aa3b, v74
	v_mul_f32_e32 v167, 0xbfb8aa3b, v75
	v_exp_f32_e32 v160, v160
	v_exp_f32_e32 v161, v161
	v_exp_f32_e32 v162, v162
	v_exp_f32_e32 v163, v163
	v_exp_f32_e32 v164, v164
	v_exp_f32_e32 v165, v165
	v_exp_f32_e32 v166, v166
	v_exp_f32_e32 v167, v167
	v_add_f32_e32 v160, 1.0, v160
	v_add_f32_e32 v161, 1.0, v161
	v_add_f32_e32 v162, 1.0, v162
	v_add_f32_e32 v163, 1.0, v163
	v_add_f32_e32 v164, 1.0, v164
	v_add_f32_e32 v165, 1.0, v165
	v_add_f32_e32 v166, 1.0, v166
	v_add_f32_e32 v167, 1.0, v167
	v_rcp_f32_e32 v160, v160
	v_rcp_f32_e32 v161, v161
	v_rcp_f32_e32 v162, v162
	v_rcp_f32_e32 v163, v163
	v_rcp_f32_e32 v164, v164
	v_rcp_f32_e32 v165, v165
	v_rcp_f32_e32 v166, v166
	v_rcp_f32_e32 v167, v167
	v_pk_mul_f32 v[76:77], v[76:77], v[160:161]
	v_pk_mul_f32 v[78:79], v[78:79], v[162:163]
	v_pk_mul_f32 v[72:73], v[72:73], v[164:165]
	v_pk_mul_f32 v[74:75], v[74:75], v[166:167]
	v_pk_mul_f32 v[68:69], v[68:69], v[76:77]
	v_pk_mul_f32 v[70:71], v[70:71], v[78:79]
	v_pk_mul_f32 v[72:73], v[64:65], v[72:73]
	v_pk_mul_f32 v[74:75], v[66:67], v[74:75]
	v_cvt_pk_bf16_f32 v64, v68, v69
	v_cvt_pk_bf16_f32 v65, v70, v71
	v_cvt_pk_bf16_f32 v66, v72, v73
	v_cvt_pk_bf16_f32 v67, v74, v75
	global_store_dwordx4 v[158:159], v[64:67], off nt
	s_waitcnt vmcnt(4)
	v_pk_add_f32 v[180:181], v[180:181], v[184:185]
	v_pk_add_f32 v[178:179], v[178:179], v[182:183]
	v_pk_add_f32 v[182:183], v[188:189], v[192:193]
	v_pk_add_f32 v[184:185], v[186:187], v[190:191]
	v_pk_add_f32 v[180:181], v[180:181], v[182:183]
	v_pk_add_f32 v[178:179], v[178:179], v[184:185]
	s_nop 0
	v_pk_mov_b32 v[182:183], v[178:179], v[180:181] op_sel:[1,0]
	v_mov_b32_e32 v179, v181
	v_pk_add_f32 v[178:179], v[182:183], v[178:179]
	s_nop 0
	v_add_f32_e32 v178, v178, v179
	v_fmamk_f32 v178, v178, 0x3a800000, v156
	v_mul_f32_e32 v179, 0x4b800000, v178
	v_cmp_gt_f32_e32 vcc, s60, v178
	s_nop 1
	v_cndmask_b32_e32 v178, v178, v179, vcc
	v_rsq_f32_e32 v180, v178
	s_nop 0
	v_mul_f32_e32 v181, 0x45800000, v180
	v_cndmask_b32_e32 v174, v180, v181, vcc
	v_pk_add_f32 v[196:197], v[196:197], v[200:201]
	v_pk_add_f32 v[194:195], v[194:195], v[198:199]
	v_pk_add_f32 v[198:199], v[204:205], v[208:209]
	v_pk_add_f32 v[200:201], v[202:203], v[206:207]
	v_pk_add_f32 v[196:197], v[196:197], v[198:199]
	v_pk_add_f32 v[194:195], v[194:195], v[200:201]
	s_nop 0
	v_pk_mov_b32 v[198:199], v[194:195], v[196:197] op_sel:[1,0]
	v_mov_b32_e32 v195, v197
	v_pk_add_f32 v[194:195], v[198:199], v[194:195]
	s_nop 0
	v_add_f32_e32 v194, v194, v195
	v_fmamk_f32 v194, v194, 0x3a800000, v156
	v_mul_f32_e32 v195, 0x4b800000, v194
	v_cmp_gt_f32_e32 vcc, s60, v194
	s_nop 1
	v_cndmask_b32_e32 v194, v194, v195, vcc
	v_rsq_f32_e32 v196, v194
	s_nop 0
	v_mul_f32_e32 v197, 0x45800000, v196
	v_cndmask_b32_e32 v175, v196, v197, vcc
	v_pk_add_f32 v[212:213], v[212:213], v[216:217]
	v_pk_add_f32 v[210:211], v[210:211], v[214:215]
	v_pk_add_f32 v[214:215], v[220:221], v[224:225]
	v_pk_add_f32 v[216:217], v[218:219], v[222:223]
	v_pk_add_f32 v[212:213], v[212:213], v[214:215]
	v_pk_add_f32 v[210:211], v[210:211], v[216:217]
	s_nop 0
	v_pk_mov_b32 v[214:215], v[210:211], v[212:213] op_sel:[1,0]
	v_mov_b32_e32 v211, v213
	v_pk_add_f32 v[210:211], v[214:215], v[210:211]
	s_nop 0
	v_add_f32_e32 v210, v210, v211
	v_fmamk_f32 v210, v210, 0x3a800000, v156
	v_mul_f32_e32 v211, 0x4b800000, v210
	v_cmp_gt_f32_e32 vcc, s60, v210
	s_nop 1
	v_cndmask_b32_e32 v210, v210, v211, vcc
	v_rsq_f32_e32 v212, v210
	s_nop 0
	v_mul_f32_e32 v213, 0x45800000, v212
	v_cndmask_b32_e32 v176, v212, v213, vcc
	v_pk_add_f32 v[228:229], v[228:229], v[232:233]
	v_pk_add_f32 v[226:227], v[226:227], v[230:231]
	v_pk_add_f32 v[230:231], v[236:237], v[240:241]
	v_pk_add_f32 v[232:233], v[234:235], v[238:239]
	v_pk_add_f32 v[228:229], v[228:229], v[230:231]
	v_pk_add_f32 v[226:227], v[226:227], v[232:233]
	s_nop 0
	v_pk_mov_b32 v[230:231], v[226:227], v[228:229] op_sel:[1,0]
	v_mov_b32_e32 v227, v229
	v_pk_add_f32 v[226:227], v[230:231], v[226:227]
	s_nop 0
	v_add_f32_e32 v226, v226, v227
	v_fmamk_f32 v226, v226, 0x3a800000, v156
	v_mul_f32_e32 v227, 0x4b800000, v226
	v_cmp_gt_f32_e32 vcc, s60, v226
	s_nop 1
	v_cndmask_b32_e32 v226, v226, v227, vcc
	v_rsq_f32_e32 v228, v226
	s_nop 0
	v_mul_f32_e32 v229, 0x45800000, v228
	v_cndmask_b32_e32 v177, v228, v229, vcc
	v_or_b32_e32 v149, 0x80, v148
	v_mad_i64_i32 v[158:159], s[8:9], v149, s61, v[144:145]
	v_lshl_add_u64 v[158:159], v[158:159], 0, v[146:147]
	v_mov_b32_e32 v168, v174
	v_pk_mul_f32 v[60:61], v[60:61], v[168:169] op_sel_hi:[1,0]
	v_pk_mul_f32 v[62:63], v[62:63], v[168:169] op_sel_hi:[1,0]
	v_pk_mul_f32 v[56:57], v[56:57], v[168:169] op_sel_hi:[1,0]
	v_pk_mul_f32 v[58:59], v[58:59], v[168:169] op_sel_hi:[1,0]
	v_pk_mul_f32 v[52:53], v[52:53], v[168:169] op_sel_hi:[1,0]
	v_pk_mul_f32 v[54:55], v[54:55], v[168:169] op_sel_hi:[1,0]
	v_pk_mul_f32 v[48:49], v[48:49], v[168:169] op_sel_hi:[1,0]
	v_pk_mul_f32 v[50:51], v[50:51], v[168:169] op_sel_hi:[1,0]
	v_mul_f32_e32 v160, 0xbfb8aa3b, v60
	v_mul_f32_e32 v161, 0xbfb8aa3b, v61
	v_mul_f32_e32 v162, 0xbfb8aa3b, v62
	v_mul_f32_e32 v163, 0xbfb8aa3b, v63
	v_mul_f32_e32 v164, 0xbfb8aa3b, v56
	v_mul_f32_e32 v165, 0xbfb8aa3b, v57
	v_mul_f32_e32 v166, 0xbfb8aa3b, v58
	v_mul_f32_e32 v167, 0xbfb8aa3b, v59
	v_exp_f32_e32 v160, v160
	v_exp_f32_e32 v161, v161
	v_exp_f32_e32 v162, v162
	v_exp_f32_e32 v163, v163
	v_exp_f32_e32 v164, v164
	v_exp_f32_e32 v165, v165
	v_exp_f32_e32 v166, v166
	v_exp_f32_e32 v167, v167
	v_add_f32_e32 v160, 1.0, v160
	v_add_f32_e32 v161, 1.0, v161
	v_add_f32_e32 v162, 1.0, v162
	v_add_f32_e32 v163, 1.0, v163
	v_add_f32_e32 v164, 1.0, v164
	v_add_f32_e32 v165, 1.0, v165
	v_add_f32_e32 v166, 1.0, v166
	v_add_f32_e32 v167, 1.0, v167
	v_rcp_f32_e32 v160, v160
	v_rcp_f32_e32 v161, v161
	v_rcp_f32_e32 v162, v162
	v_rcp_f32_e32 v163, v163
	v_rcp_f32_e32 v164, v164
	v_rcp_f32_e32 v165, v165
	v_rcp_f32_e32 v166, v166
	v_rcp_f32_e32 v167, v167
	v_pk_mul_f32 v[60:61], v[60:61], v[160:161]
	v_pk_mul_f32 v[62:63], v[62:63], v[162:163]
	v_pk_mul_f32 v[56:57], v[56:57], v[164:165]
	v_pk_mul_f32 v[58:59], v[58:59], v[166:167]
	v_pk_mul_f32 v[52:53], v[52:53], v[60:61]
	v_pk_mul_f32 v[54:55], v[54:55], v[62:63]
	v_pk_mul_f32 v[56:57], v[48:49], v[56:57]
	v_pk_mul_f32 v[58:59], v[50:51], v[58:59]
	v_cvt_pk_bf16_f32 v48, v52, v53
	v_cvt_pk_bf16_f32 v49, v54, v55
	v_cvt_pk_bf16_f32 v50, v56, v57
	v_cvt_pk_bf16_f32 v51, v58, v59
	global_store_dwordx4 v[158:159], v[48:51], off nt
	v_or_b32_e32 v149, 0x90, v148
	v_mad_i64_i32 v[158:159], s[8:9], v149, s61, v[144:145]
	v_lshl_add_u64 v[158:159], v[158:159], 0, v[146:147]
	v_mov_b32_e32 v168, v175
	v_pk_mul_f32 v[44:45], v[44:45], v[168:169] op_sel_hi:[1,0]
	v_pk_mul_f32 v[46:47], v[46:47], v[168:169] op_sel_hi:[1,0]
	v_pk_mul_f32 v[40:41], v[40:41], v[168:169] op_sel_hi:[1,0]
	v_pk_mul_f32 v[42:43], v[42:43], v[168:169] op_sel_hi:[1,0]
	v_pk_mul_f32 v[36:37], v[36:37], v[168:169] op_sel_hi:[1,0]
	v_pk_mul_f32 v[38:39], v[38:39], v[168:169] op_sel_hi:[1,0]
	v_pk_mul_f32 v[32:33], v[32:33], v[168:169] op_sel_hi:[1,0]
	v_pk_mul_f32 v[34:35], v[34:35], v[168:169] op_sel_hi:[1,0]
	v_mul_f32_e32 v160, 0xbfb8aa3b, v44
	v_mul_f32_e32 v161, 0xbfb8aa3b, v45
	v_mul_f32_e32 v162, 0xbfb8aa3b, v46
	v_mul_f32_e32 v163, 0xbfb8aa3b, v47
	v_mul_f32_e32 v164, 0xbfb8aa3b, v40
	v_mul_f32_e32 v165, 0xbfb8aa3b, v41
	v_mul_f32_e32 v166, 0xbfb8aa3b, v42
	v_mul_f32_e32 v167, 0xbfb8aa3b, v43
	v_exp_f32_e32 v160, v160
	v_exp_f32_e32 v161, v161
	v_exp_f32_e32 v162, v162
	v_exp_f32_e32 v163, v163
	v_exp_f32_e32 v164, v164
	v_exp_f32_e32 v165, v165
	v_exp_f32_e32 v166, v166
	v_exp_f32_e32 v167, v167
	v_add_f32_e32 v160, 1.0, v160
	v_add_f32_e32 v161, 1.0, v161
	v_add_f32_e32 v162, 1.0, v162
	v_add_f32_e32 v163, 1.0, v163
	v_add_f32_e32 v164, 1.0, v164
	v_add_f32_e32 v165, 1.0, v165
	v_add_f32_e32 v166, 1.0, v166
	v_add_f32_e32 v167, 1.0, v167
	v_rcp_f32_e32 v160, v160
	v_rcp_f32_e32 v161, v161
	v_rcp_f32_e32 v162, v162
	v_rcp_f32_e32 v163, v163
	v_rcp_f32_e32 v164, v164
	v_rcp_f32_e32 v165, v165
	v_rcp_f32_e32 v166, v166
	v_rcp_f32_e32 v167, v167
	v_pk_mul_f32 v[44:45], v[44:45], v[160:161]
	v_pk_mul_f32 v[46:47], v[46:47], v[162:163]
	v_pk_mul_f32 v[40:41], v[40:41], v[164:165]
	v_pk_mul_f32 v[42:43], v[42:43], v[166:167]
	v_pk_mul_f32 v[36:37], v[36:37], v[44:45]
	v_pk_mul_f32 v[38:39], v[38:39], v[46:47]
	v_pk_mul_f32 v[40:41], v[32:33], v[40:41]
	v_pk_mul_f32 v[42:43], v[34:35], v[42:43]
	v_cvt_pk_bf16_f32 v32, v36, v37
	v_cvt_pk_bf16_f32 v33, v38, v39
	v_cvt_pk_bf16_f32 v34, v40, v41
	v_cvt_pk_bf16_f32 v35, v42, v43
	global_store_dwordx4 v[158:159], v[32:35], off nt
	v_or_b32_e32 v149, 0xa0, v148
	v_mad_i64_i32 v[158:159], s[8:9], v149, s61, v[144:145]
	v_lshl_add_u64 v[158:159], v[158:159], 0, v[146:147]
	v_mov_b32_e32 v168, v176
	v_pk_mul_f32 v[28:29], v[28:29], v[168:169] op_sel_hi:[1,0]
	v_pk_mul_f32 v[30:31], v[30:31], v[168:169] op_sel_hi:[1,0]
	v_pk_mul_f32 v[24:25], v[24:25], v[168:169] op_sel_hi:[1,0]
	v_pk_mul_f32 v[26:27], v[26:27], v[168:169] op_sel_hi:[1,0]
	v_pk_mul_f32 v[20:21], v[20:21], v[168:169] op_sel_hi:[1,0]
	v_pk_mul_f32 v[22:23], v[22:23], v[168:169] op_sel_hi:[1,0]
	v_pk_mul_f32 v[16:17], v[16:17], v[168:169] op_sel_hi:[1,0]
	v_pk_mul_f32 v[18:19], v[18:19], v[168:169] op_sel_hi:[1,0]
	v_mul_f32_e32 v160, 0xbfb8aa3b, v28
	v_mul_f32_e32 v161, 0xbfb8aa3b, v29
	v_mul_f32_e32 v162, 0xbfb8aa3b, v30
	v_mul_f32_e32 v163, 0xbfb8aa3b, v31
	v_mul_f32_e32 v164, 0xbfb8aa3b, v24
	v_mul_f32_e32 v165, 0xbfb8aa3b, v25
	v_mul_f32_e32 v166, 0xbfb8aa3b, v26
	v_mul_f32_e32 v167, 0xbfb8aa3b, v27
	v_exp_f32_e32 v160, v160
	v_exp_f32_e32 v161, v161
	v_exp_f32_e32 v162, v162
	v_exp_f32_e32 v163, v163
	v_exp_f32_e32 v164, v164
	v_exp_f32_e32 v165, v165
	v_exp_f32_e32 v166, v166
	v_exp_f32_e32 v167, v167
	v_add_f32_e32 v160, 1.0, v160
	v_add_f32_e32 v161, 1.0, v161
	v_add_f32_e32 v162, 1.0, v162
	v_add_f32_e32 v163, 1.0, v163
	v_add_f32_e32 v164, 1.0, v164
	v_add_f32_e32 v165, 1.0, v165
	v_add_f32_e32 v166, 1.0, v166
	v_add_f32_e32 v167, 1.0, v167
	v_rcp_f32_e32 v160, v160
	v_rcp_f32_e32 v161, v161
	v_rcp_f32_e32 v162, v162
	v_rcp_f32_e32 v163, v163
	v_rcp_f32_e32 v164, v164
	v_rcp_f32_e32 v165, v165
	v_rcp_f32_e32 v166, v166
	v_rcp_f32_e32 v167, v167
	v_pk_mul_f32 v[28:29], v[28:29], v[160:161]
	v_pk_mul_f32 v[30:31], v[30:31], v[162:163]
	v_pk_mul_f32 v[24:25], v[24:25], v[164:165]
	v_pk_mul_f32 v[26:27], v[26:27], v[166:167]
	v_pk_mul_f32 v[20:21], v[20:21], v[28:29]
	v_pk_mul_f32 v[22:23], v[22:23], v[30:31]
	v_pk_mul_f32 v[24:25], v[16:17], v[24:25]
	v_pk_mul_f32 v[26:27], v[18:19], v[26:27]
	v_cvt_pk_bf16_f32 v16, v20, v21
	v_cvt_pk_bf16_f32 v17, v22, v23
	v_cvt_pk_bf16_f32 v18, v24, v25
	v_cvt_pk_bf16_f32 v19, v26, v27
	global_store_dwordx4 v[158:159], v[16:19], off nt
	v_or_b32_e32 v149, 0xb0, v148
	v_mad_i64_i32 v[158:159], s[8:9], v149, s61, v[144:145]
	v_lshl_add_u64 v[158:159], v[158:159], 0, v[146:147]
	v_mov_b32_e32 v168, v177
	v_pk_mul_f32 v[12:13], v[12:13], v[168:169] op_sel_hi:[1,0]
	v_pk_mul_f32 v[14:15], v[14:15], v[168:169] op_sel_hi:[1,0]
	v_pk_mul_f32 v[8:9], v[8:9], v[168:169] op_sel_hi:[1,0]
	v_pk_mul_f32 v[10:11], v[10:11], v[168:169] op_sel_hi:[1,0]
	v_pk_mul_f32 v[4:5], v[4:5], v[168:169] op_sel_hi:[1,0]
	v_pk_mul_f32 v[6:7], v[6:7], v[168:169] op_sel_hi:[1,0]
	v_pk_mul_f32 v[0:1], v[0:1], v[168:169] op_sel_hi:[1,0]
	v_pk_mul_f32 v[2:3], v[2:3], v[168:169] op_sel_hi:[1,0]
	v_mul_f32_e32 v160, 0xbfb8aa3b, v12
	v_mul_f32_e32 v161, 0xbfb8aa3b, v13
	v_mul_f32_e32 v162, 0xbfb8aa3b, v14
	v_mul_f32_e32 v163, 0xbfb8aa3b, v15
	v_mul_f32_e32 v164, 0xbfb8aa3b, v8
	v_mul_f32_e32 v165, 0xbfb8aa3b, v9
	v_mul_f32_e32 v166, 0xbfb8aa3b, v10
	v_mul_f32_e32 v167, 0xbfb8aa3b, v11
	v_exp_f32_e32 v160, v160
	v_exp_f32_e32 v161, v161
	v_exp_f32_e32 v162, v162
	v_exp_f32_e32 v163, v163
	v_exp_f32_e32 v164, v164
	v_exp_f32_e32 v165, v165
	v_exp_f32_e32 v166, v166
	v_exp_f32_e32 v167, v167
	v_add_f32_e32 v160, 1.0, v160
	v_add_f32_e32 v161, 1.0, v161
	v_add_f32_e32 v162, 1.0, v162
	v_add_f32_e32 v163, 1.0, v163
	v_add_f32_e32 v164, 1.0, v164
	v_add_f32_e32 v165, 1.0, v165
	v_add_f32_e32 v166, 1.0, v166
	v_add_f32_e32 v167, 1.0, v167
	v_rcp_f32_e32 v160, v160
	v_rcp_f32_e32 v161, v161
	v_rcp_f32_e32 v162, v162
	v_rcp_f32_e32 v163, v163
	v_rcp_f32_e32 v164, v164
	v_rcp_f32_e32 v165, v165
	v_rcp_f32_e32 v166, v166
	v_rcp_f32_e32 v167, v167
	v_pk_mul_f32 v[12:13], v[12:13], v[160:161]
	v_pk_mul_f32 v[14:15], v[14:15], v[162:163]
	v_pk_mul_f32 v[8:9], v[8:9], v[164:165]
	v_pk_mul_f32 v[10:11], v[10:11], v[166:167]
	v_pk_mul_f32 v[4:5], v[4:5], v[12:13]
	v_pk_mul_f32 v[6:7], v[6:7], v[14:15]
	v_pk_mul_f32 v[8:9], v[0:1], v[8:9]
	v_pk_mul_f32 v[10:11], v[2:3], v[10:11]
	v_cvt_pk_bf16_f32 v0, v4, v5
	v_cvt_pk_bf16_f32 v1, v6, v7
	v_cvt_pk_bf16_f32 v2, v8, v9
	v_cvt_pk_bf16_f32 v3, v10, v11
	global_store_dwordx4 v[158:159], v[0:3], off nt
	s_andn2_b64 vcc, exec, s[6:7]
	s_mov_b64 s[6:7], -1
	s_cbranch_vccnz .LBB0_1230
	s_andn2_b64 vcc, exec, s[0:1]
	s_cbranch_vccnz .LBB0_1229
	s_barrier
	s_branch .LBB0_1229
